# SB5: every 8th arriver of an XCD pre-flushes the L2 while it waits
# speedup vs baseline: 1.0009x; 1.0009x over previous
.LBB0_556:
	s_cmp_gt_i32 s95, 6
	s_cselect_b64 s[0:1], -1, 0
	s_and_b64 s[4:5], s[58:59], s[0:1]
	s_andn2_b64 vcc, exec, s[4:5]
	s_cbranch_vccnz .LBB0_610
	s_waitcnt vmcnt(0) lgkmcnt(0)
	s_barrier
	s_mov_b64 s[4:5], exec
	v_readlane_b32 s6, v246, 2
	v_readlane_b32 s7, v246, 3
	s_and_b64 s[6:7], s[4:5], s[6:7]
	s_mov_b64 exec, s[6:7]
	s_cbranch_execz .Lsb5_end
	s_lshl_b32 s8, s33, 8
	s_add_u32 s8, s8, 0x56080
	s_add_u32 s8, s92, s8
	s_addc_u32 s9, s93, 0
	v_mov_b32_e32 v2, 0
	v_mov_b32_e32 v3, 1
	global_atomic_add v3, v2, v3, s[8:9] sc0
	s_add_u32 s8, s92, 0x57100
	s_addc_u32 s9, s93, 0
	v_readlane_b32 s18, v246, 8
	s_waitcnt vmcnt(0)
	v_readfirstlane_b32 s19, v3
	s_add_u32 s19, s19, 1
	s_and_b32 s20, s19, 7
	s_cmp_eq_u32 s20, 0
	s_cselect_b32 s21, 1, 0
	s_cmp_eq_u32 s19, s18
	s_cselect_b32 s22, 1, 0
	s_or_b32 s21, s21, s22
	s_cmp_eq_u32 s21, 0
	s_cbranch_scc1 .Lsb5_poll0
	buffer_wbl2 sc1
	s_waitcnt vmcnt(0)
	s_cmp_eq_u32 s22, 0
	s_cbranch_scc1 .Lsb5_poll0
	v_mov_b32_e32 v3, s18
	global_atomic_add v2, v3, s[8:9]
